# v29 + forgetting-attention loop back edge rotated (common case one taken branch)
# baseline (speedup 1.0000x reference)
; template <int TYPE  >
; __device__ __forceinline__ void attn_item(const Params& P, const int b, const int h, const int qt, LAS unsigned char* lds) {
;     ...
;     for (int it = 0; it < NT; ++it) {
;         const int kt = AT_TILE(it);
;         if (it + 1 < NT) at_waitv<NI>(); else at_waitv<0>();
;     ...
;         so = (so == 2 * SLOT) ? 0u : so + SLOT; so2 = (so2 == 2 * SLOT) ? 0u : so2 + SLOT;
.LBB0_1160:
	s_add_i32 s8, s13, 0x8800
	s_cmp_lg_u32 s13, 0x11000
	s_cselect_b32 s13, s8, 0
	s_add_i32 s8, s14, 0x8800
	s_cmp_lg_u32 s14, 0x11000
	s_cselect_b32 s14, s8, 0
	s_mov_b64 s[8:9], 0x100
	v_lshl_add_u64 v[146:147], v[146:147], 0, s[8:9]
	s_mov_b64 s[8:9], 0x20000
	v_lshl_add_u64 v[148:149], v[148:149], 0, s[20:21]
	v_lshl_add_u64 v[150:151], v[150:151], 0, s[20:21]
	v_lshl_add_u64 v[152:153], v[152:153], 0, s[8:9]
	s_cmp_lg_u32 s36, s15
	v_lshl_add_u64 v[154:155], v[154:155], 0, s[8:9]
	s_cbranch_scc0 .LBB0_1086
	v_mov_b32_e32 v196, v66
	s_mov_b32 s16, s15
	s_add_i32 s15, s16, 1
	s_cmp_ge_u32 s15, s36
	s_mov_b64 s[8:9], -1
	s_cbranch_scc0 .LBB0_1149
	s_branch .LBB0_1148
